# LDS-DMA placement: V^T pieces issue 4 (GQA) / 6 (MLA) MFMA gaps after the K pieces
# baseline (speedup 1.0000x reference)
;   DI void gload_k(int t) {
;     const int row0 = rowk0 + t * 64;
;     const u16* kt = Kb + (size_t)row0 * kpitch;
;     const u16* pt = KPEb + (size_t)row0 * 32;
; #pragma unroll
;     for (int q = 0; q < NKL; ++q) {
;       const int c = tid + 256 * q, cc = c % KCH;
;       rk[q] = ldg16(((DQK == 96 && cc >= 8) ? pt : kt) + koff[q]);
;     }
;   template <int PAR>
;   DI void step(int t, f32x16 (&cur)[2], f32x16 (&nxt)[2]) {
;     if (t + 1 < nt) sstore_k(PAR ^ 1);
;     if (t > 0) sstore_v(PAR);
;     __syncthreads();
;     if (t + 1 < nt) qk(PAR ^ 1, nxt);
;     float mx = fmaxf(cur[0][0], cur[1][0]);
; #pragma unroll
;     for (int i = 1; i < 16; ++i) mx = fmaxf(fmaxf(cur[0][i], cur[1][i]), mx);
;     if (__builtin_amdgcn_ballot_w64(mx > ATT_THR) != 0ull) {
;       asm volatile("" ::: "memory");
;       mx = fmaxf(mx, xhalf(mx));
;       const float want = mref + fmaxf(mx, 0.f);
;       const float mn = __uint_as_float(pack2(want, 0.f) << 16);
;       const float d = mn - mref;
;       const float alpha = __builtin_amdgcn_exp2f(-d);
;       mref = mn;
;       l *= alpha;
; #pragma unroll
;       for (int a = 0; a < 2; ++a)
; #pragma unroll
;         for (int i = 0; i < 16; ++i) { o[a][i] *= alpha; cur[a][i] -= d; nxt[a][i] -= d; }
;       u32x4 q4 = {h == 0 ? (pack2(-mn, 0.f) & 0xffffu) : 0u, 0u, 0u, 0u};
;       qm = __builtin_bit_cast(bf16x8, q4);
;     }
;     float psum = 0.f;
; #pragma unroll
;     for (int kb2 = 0; kb2 < 2; ++kb2)
; #pragma unroll
;       for (int i = 0; i < 16; ++i) { const float pv = __builtin_amdgcn_exp2f(cur[kb2][i]); cur[kb2][i] = pv; psum += pv; }
;     l += psum;
;     if (t + 2 < nt) gload_k(t + 2);
;     if (t + 1 < nt) gload_v(t + 1);
;     const u16* vb = sV + PAR * VBUF + r * GP + h * 8;
; #pragma unroll
;     for (int kb2 = 0; kb2 < 2; ++kb2)
; #pragma unroll
;       for (int s2 = 0; s2 < 2; ++s2) {
;         u32x4 pk = {pack2(cur[kb2][8 * s2], cur[kb2][8 * s2 + 1]), pack2(cur[kb2][8 * s2 + 2], cur[kb2][8 * s2 + 3]),
;                     pack2(cur[kb2][8 * s2 + 4], cur[kb2][8 * s2 + 5]), pack2(cur[kb2][8 * s2 + 6], cur[kb2][8 * s2 + 7])};
;         const bf16x8 pf = __builtin_bit_cast(bf16x8, pk);
; #pragma unroll
;         for (int db = 0; db < 2; ++db) {
;           const bf16x8 a = *(const bf16x8*)(vb + db * 32 * GP + kb2 * 32 + s2 * 16);
;           o[db] = MFMA(a, pf, o[db]);
;         }
;       }
;   }
.Lgf_skipKA:
	ds_read_b128 v[96:99], v156 offset:18432
	ds_read_b128 v[100:103], v156 offset:22528
	ds_read_b128 v[104:107], v157 offset:18432
	ds_read_b128 v[108:111], v157 offset:22528
	v_mfma_f32_32x32x16_bf16 v[80:95], v[112:115], v[144:147], v[80:95]
	ds_read_b128 v[112:115], v158 offset:18432
	v_exp_f32_e32 v63, v63
	v_add_f32_e32 v183, v61, v183
	v_cvt_pk_bf16_f32 v56, v56, v57
	v_add_f32_e32 v182, v62, v182
	v_cvt_pk_bf16_f32 v57, v58, v59
	v_add_f32_e32 v183, v63, v183
	v_mfma_f32_32x32x16_bf16 v[64:79], v[116:119], v[144:147], v[64:79]
	ds_read_b128 v[116:119], v158 offset:22528
	v_cvt_pk_bf16_f32 v58, v60, v61
	v_cvt_pk_bf16_f32 v59, v62, v63
	v_exp_f32_e32 v32, v32
	v_exp_f32_e32 v33, v33
	v_exp_f32_e32 v34, v34
	v_add_f32_e32 v182, v32, v182
	v_mfma_f32_32x32x16_bf16 v[80:95], v[120:123], v[148:151], v[80:95]
	ds_read_b128 v[120:123], v159 offset:18432
	v_exp_f32_e32 v35, v35
	v_add_f32_e32 v183, v33, v183
	v_exp_f32_e32 v36, v36
	v_add_f32_e32 v182, v34, v182
	v_exp_f32_e32 v37, v37
	v_add_f32_e32 v183, v35, v183
	v_mfma_f32_32x32x16_bf16 v[64:79], v[124:127], v[148:151], v[64:79]
	ds_read_b128 v[124:127], v159 offset:22528
	v_exp_f32_e32 v38, v38
	v_add_f32_e32 v182, v36, v182
	v_exp_f32_e32 v39, v39
	v_add_f32_e32 v183, v37, v183
	v_cvt_pk_bf16_f32 v32, v32, v33
	v_add_f32_e32 v182, v38, v182
	s_add_i32 m0, s46, 27648
	s_nop 0
	global_load_lds_dwordx4 v[160:161], off
	global_load_lds_dwordx4 v[162:163], off offset:1024
	v_lshl_add_u64 v[160:161], v[160:161], 0, s[84:85]
	v_lshl_add_u64 v[162:163], v[162:163], 0, s[84:85]
	s_waitcnt lgkmcnt(4)
	v_mfma_f32_32x32x16_bf16 v[16:31], v[96:99], v[48:51], v[16:31]
	ds_read_b128 v[96:99], v152
	v_cvt_pk_bf16_f32 v33, v34, v35
	v_add_f32_e32 v183, v39, v183
	v_cvt_pk_bf16_f32 v34, v36, v37
	v_cvt_pk_bf16_f32 v35, v38, v39
	v_exp_f32_e32 v40, v40
	v_mfma_f32_32x32x16_bf16 v[0:15], v[100:103], v[48:51], v[0:15]
	ds_read_b128 v[100:103], v152 offset:4096
	v_exp_f32_e32 v41, v41
	v_exp_f32_e32 v42, v42
	v_add_f32_e32 v182, v40, v182
	v_exp_f32_e32 v43, v43
	v_add_f32_e32 v183, v41, v183
	v_mfma_f32_32x32x16_bf16 v[16:31], v[104:107], v[56:59], v[16:31]
	ds_read_b128 v[104:107], v153
	v_exp_f32_e32 v44, v44
	v_add_f32_e32 v182, v42, v182
	v_exp_f32_e32 v45, v45
	v_add_f32_e32 v183, v43, v183
	v_exp_f32_e32 v46, v46
	v_mfma_f32_32x32x16_bf16 v[0:15], v[108:111], v[56:59], v[0:15]
	ds_read_b128 v[108:111], v153 offset:4096
	v_add_f32_e32 v182, v44, v182
	v_exp_f32_e32 v47, v47
	v_add_f32_e32 v183, v45, v183
	v_cvt_pk_bf16_f32 v40, v40, v41
	v_add_f32_e32 v182, v46, v182
	s_waitcnt lgkmcnt(4)
	v_mfma_f32_32x32x16_bf16 v[16:31], v[112:115], v[32:35], v[16:31]
	ds_read_b128 v[112:115], v154
	v_cvt_pk_bf16_f32 v41, v42, v43
	v_add_f32_e32 v183, v47, v183
	v_cvt_pk_bf16_f32 v42, v44, v45
	v_cvt_pk_bf16_f32 v43, v46, v47
	v_max3_f32 v128, v80, v64, v81
	v_mfma_f32_32x32x16_bf16 v[0:15], v[116:119], v[32:35], v[0:15]
	ds_read_b128 v[116:119], v154 offset:4096
	v_max3_f32 v172, v65, v82, v66
	v_max3_f32 v128, v83, v67, v128
	v_max3_f32 v172, v84, v68, v172
	v_max3_f32 v128, v85, v69, v128
	v_max3_f32 v172, v86, v70, v172
	v_mfma_f32_32x32x16_bf16 v[16:31], v[120:123], v[40:43], v[16:31]
	ds_read_b128 v[120:123], v155
	v_max3_f32 v128, v87, v71, v128
	v_max3_f32 v172, v88, v72, v172
	v_max3_f32 v128, v89, v73, v128
	v_max3_f32 v172, v90, v74, v172
	v_max3_f32 v128, v91, v75, v128
	v_mfma_f32_32x32x16_bf16 v[0:15], v[124:127], v[40:43], v[0:15]
	ds_read_b128 v[124:127], v155 offset:4096
	v_max3_f32 v172, v92, v76, v172
	v_max3_f32 v128, v93, v77, v128
	v_max3_f32 v172, v94, v78, v172
	v_max3_f32 v128, v95, v79, v128
	v_max_f32_e32 v128, v128, v172
	v_cmp_lt_f32_e32 vcc, s65, v128
	s_cbranch_vccnz .Lgf_rareB

; #define MFMA(a, b, c) __builtin_amdgcn_mfma_f32_32x32x16_bf16((a), (b), (c), 0, 0, 0)
; DI float xhalf(float v) { return __shfl_xor(v, 32); }
;   DI void gload_v(int t) {
;     const u16* vt = Vt + (rowk0 + t * 64);
; #pragma unroll
;     for (int q = 0; q < 2; ++q) rv[q] = ldg16(vt + voff[q]);
;   }
;   template <int PAR>
;   DI void step(int t, f32x16 (&cur)[2], f32x16 (&nxt)[2]) {
;     if (t + 1 < nt) sstore_k(PAR ^ 1);
;     if (t > 0) sstore_v(PAR);
;     __syncthreads();
;     if (t + 1 < nt) qk(PAR ^ 1, nxt);
;     float mx = fmaxf(cur[0][0], cur[1][0]);
; #pragma unroll
;     for (int i = 1; i < 16; ++i) mx = fmaxf(fmaxf(cur[0][i], cur[1][i]), mx);
;     if (__builtin_amdgcn_ballot_w64(mx > ATT_THR) != 0ull) {
;       asm volatile("" ::: "memory");
;       mx = fmaxf(mx, xhalf(mx));
;       const float want = mref + fmaxf(mx, 0.f);
;       const float mn = __uint_as_float(pack2(want, 0.f) << 16);
;       const float d = mn - mref;
;       const float alpha = __builtin_amdgcn_exp2f(-d);
;       mref = mn;
;       l *= alpha;
; #pragma unroll
;       for (int a = 0; a < 2; ++a)
; #pragma unroll
;         for (int i = 0; i < 16; ++i) { o[a][i] *= alpha; cur[a][i] -= d; nxt[a][i] -= d; }
;       u32x4 q4 = {h == 0 ? (pack2(-mn, 0.f) & 0xffffu) : 0u, 0u, 0u, 0u};
;       qm = __builtin_bit_cast(bf16x8, q4);
;     }
;     float psum = 0.f;
; #pragma unroll
;     for (int kb2 = 0; kb2 < 2; ++kb2)
; #pragma unroll
;       for (int i = 0; i < 16; ++i) { const float pv = __builtin_amdgcn_exp2f(cur[kb2][i]); cur[kb2][i] = pv; psum += pv; }
;     l += psum;
;     if (t + 2 < nt) gload_k(t + 2);
;     if (t + 1 < nt) gload_v(t + 1);
;     const u16* vb = sV + PAR * VBUF + r * GP + h * 8;
; #pragma unroll
;     for (int kb2 = 0; kb2 < 2; ++kb2)
; #pragma unroll
;       for (int s2 = 0; s2 < 2; ++s2) {
;         u32x4 pk = {pack2(cur[kb2][8 * s2], cur[kb2][8 * s2 + 1]), pack2(cur[kb2][8 * s2 + 2], cur[kb2][8 * s2 + 3]),
;                     pack2(cur[kb2][8 * s2 + 4], cur[kb2][8 * s2 + 5]), pack2(cur[kb2][8 * s2 + 6], cur[kb2][8 * s2 + 7])};
;         const bf16x8 pf = __builtin_bit_cast(bf16x8, pk);
; #pragma unroll
;         for (int db = 0; db < 2; ++db) {
;           const bf16x8 a = *(const bf16x8*)(vb + db * 32 * GP + kb2 * 32 + s2 * 16);
;           o[db] = MFMA(a, pf, o[db]);
;         }
;       }
;   }
.Lgf_skipKB:
	ds_read_b128 v[96:99], v156 offset:27648
	ds_read_b128 v[100:103], v156 offset:31744
	ds_read_b128 v[104:107], v157 offset:27648
	ds_read_b128 v[108:111], v157 offset:31744
	v_mfma_f32_32x32x16_bf16 v[48:63], v[112:115], v[144:147], v[48:63]
	ds_read_b128 v[112:115], v158 offset:27648
	v_exp_f32_e32 v95, v95
	v_add_f32_e32 v183, v93, v183
	v_cvt_pk_bf16_f32 v88, v88, v89
	v_add_f32_e32 v182, v94, v182
	v_cvt_pk_bf16_f32 v89, v90, v91
	v_add_f32_e32 v183, v95, v183
	v_mfma_f32_32x32x16_bf16 v[32:47], v[116:119], v[144:147], v[32:47]
	ds_read_b128 v[116:119], v158 offset:31744
	v_cvt_pk_bf16_f32 v90, v92, v93
	v_cvt_pk_bf16_f32 v91, v94, v95
	v_exp_f32_e32 v64, v64
	v_exp_f32_e32 v65, v65
	v_exp_f32_e32 v66, v66
	v_add_f32_e32 v182, v64, v182
	v_mfma_f32_32x32x16_bf16 v[48:63], v[120:123], v[148:151], v[48:63]
	ds_read_b128 v[120:123], v159 offset:27648
	v_exp_f32_e32 v67, v67
	v_add_f32_e32 v183, v65, v183
	v_exp_f32_e32 v68, v68
	v_add_f32_e32 v182, v66, v182
	v_exp_f32_e32 v69, v69
	v_add_f32_e32 v183, v67, v183
	v_mfma_f32_32x32x16_bf16 v[32:47], v[124:127], v[148:151], v[32:47]
	ds_read_b128 v[124:127], v159 offset:31744
	v_exp_f32_e32 v70, v70
	v_add_f32_e32 v182, v68, v182
	v_exp_f32_e32 v71, v71
	v_add_f32_e32 v183, v69, v183
	v_cvt_pk_bf16_f32 v64, v64, v65
	v_add_f32_e32 v182, v70, v182
	s_cmp_ge_u32 s45, s19
	s_cbranch_scc1 .Lgf_lastVB
	s_add_i32 m0, s46, 18432
	s_nop 0
	global_load_lds_dwordx4 v[164:165], off
	global_load_lds_dwordx4 v[166:167], off offset:1024
	v_lshl_add_u64 v[164:165], v[164:165], 0, s[84:85]
	v_lshl_add_u64 v[166:167], v[166:167], 0, s[84:85]
	s_branch .Lgf_skipVB

; #define MFMA(a, b, c) __builtin_amdgcn_mfma_f32_32x32x16_bf16((a), (b), (c), 0, 0, 0)
; DI unsigned pack2(float a, float b) { f32x2v f = {a, b}; bf16x2v v = __builtin_convertvector(f, bf16x2v); return __builtin_bit_cast(unsigned, v); }
; DI float xhalf(float v) { return __shfl_xor(v, 32); }
;   template <int PAR>
;   DI void step(int t, f32x16 (&cur)[2], f32x16 (&nxt)[2]) {
;     if (t + 1 < nt) sstore_k(PAR ^ 1);
;     if (t > 0) sstore_v(PAR);
;     __syncthreads();
;     if (t + 1 < nt) qk(PAR ^ 1, nxt);
;     float mx = fmaxf(cur[0][0], cur[1][0]);
; #pragma unroll
;     for (int i = 1; i < 16; ++i) mx = fmaxf(fmaxf(cur[0][i], cur[1][i]), mx);
;     if (__builtin_amdgcn_ballot_w64(mx > ATT_THR) != 0ull) {
;       asm volatile("" ::: "memory");
;       mx = fmaxf(mx, xhalf(mx));
;       const float want = mref + fmaxf(mx, 0.f);
;       const float mn = __uint_as_float(pack2(want, 0.f) << 16);
;       const float d = mn - mref;
;       const float alpha = __builtin_amdgcn_exp2f(-d);
;       mref = mn;
;       l *= alpha;
; #pragma unroll
;       for (int a = 0; a < 2; ++a)
; #pragma unroll
;         for (int i = 0; i < 16; ++i) { o[a][i] *= alpha; cur[a][i] -= d; nxt[a][i] -= d; }
;       u32x4 q4 = {h == 0 ? (pack2(-mn, 0.f) & 0xffffu) : 0u, 0u, 0u, 0u};
;       qm = __builtin_bit_cast(bf16x8, q4);
;     }
;     float psum = 0.f;
; #pragma unroll
;     for (int kb2 = 0; kb2 < 2; ++kb2)
; #pragma unroll
;       for (int i = 0; i < 16; ++i) { const float pv = __builtin_amdgcn_exp2f(cur[kb2][i]); cur[kb2][i] = pv; psum += pv; }
;     l += psum;
;     if (t + 2 < nt) gload_k(t + 2);
;     if (t + 1 < nt) gload_v(t + 1);
;     const u16* vb = sV + PAR * VBUF + r * GP + h * 8;
; #pragma unroll
;     for (int kb2 = 0; kb2 < 2; ++kb2)
; #pragma unroll
;       for (int s2 = 0; s2 < 2; ++s2) {
;         u32x4 pk = {pack2(cur[kb2][8 * s2], cur[kb2][8 * s2 + 1]), pack2(cur[kb2][8 * s2 + 2], cur[kb2][8 * s2 + 3]),
;                     pack2(cur[kb2][8 * s2 + 4], cur[kb2][8 * s2 + 5]), pack2(cur[kb2][8 * s2 + 6], cur[kb2][8 * s2 + 7])};
;         const bf16x8 pf = __builtin_bit_cast(bf16x8, pk);
; #pragma unroll
;         for (int db = 0; db < 2; ++db) {
;           const bf16x8 a = *(const bf16x8*)(vb + db * 32 * GP + kb2 * 32 + s2 * 16);
;           o[db] = MFMA(a, pf, o[db]);
;         }
;       }
;   }
.Lgf_skipVB:
	s_waitcnt lgkmcnt(4)
	v_mfma_f32_32x32x16_bf16 v[16:31], v[96:99], v[80:83], v[16:31]
	ds_read_b128 v[96:99], v152 offset:9216
	v_cvt_pk_bf16_f32 v65, v66, v67
	v_add_f32_e32 v183, v71, v183
	v_cvt_pk_bf16_f32 v66, v68, v69
	v_cvt_pk_bf16_f32 v67, v70, v71
	v_exp_f32_e32 v72, v72
	v_mfma_f32_32x32x16_bf16 v[0:15], v[100:103], v[80:83], v[0:15]
	ds_read_b128 v[100:103], v152 offset:13312
	v_exp_f32_e32 v73, v73
	v_exp_f32_e32 v74, v74
	v_add_f32_e32 v182, v72, v182
	v_exp_f32_e32 v75, v75
	v_add_f32_e32 v183, v73, v183
	v_mfma_f32_32x32x16_bf16 v[16:31], v[104:107], v[88:91], v[16:31]
	ds_read_b128 v[104:107], v153 offset:9216
	v_exp_f32_e32 v76, v76
	v_add_f32_e32 v182, v74, v182
	v_exp_f32_e32 v77, v77
	v_add_f32_e32 v183, v75, v183
	v_exp_f32_e32 v78, v78
	v_mfma_f32_32x32x16_bf16 v[0:15], v[108:111], v[88:91], v[0:15]
	ds_read_b128 v[108:111], v153 offset:13312
	v_add_f32_e32 v182, v76, v182
	v_exp_f32_e32 v79, v79
	v_add_f32_e32 v183, v77, v183
	v_cvt_pk_bf16_f32 v72, v72, v73
	v_add_f32_e32 v182, v78, v182
	s_waitcnt lgkmcnt(4)
	v_mfma_f32_32x32x16_bf16 v[16:31], v[112:115], v[64:67], v[16:31]
	ds_read_b128 v[112:115], v154 offset:9216
	v_cvt_pk_bf16_f32 v73, v74, v75
	v_add_f32_e32 v183, v79, v183
	v_cvt_pk_bf16_f32 v74, v76, v77
	v_cvt_pk_bf16_f32 v75, v78, v79
	v_max3_f32 v128, v48, v32, v49
	v_mfma_f32_32x32x16_bf16 v[0:15], v[116:119], v[64:67], v[0:15]
	ds_read_b128 v[116:119], v154 offset:13312
	v_max3_f32 v172, v33, v50, v34
	v_max3_f32 v128, v51, v35, v128
	v_max3_f32 v172, v52, v36, v172
	v_max3_f32 v128, v53, v37, v128
	v_max3_f32 v172, v54, v38, v172
	v_mfma_f32_32x32x16_bf16 v[16:31], v[120:123], v[72:75], v[16:31]
	ds_read_b128 v[120:123], v155 offset:9216
	v_max3_f32 v128, v55, v39, v128
	v_max3_f32 v172, v56, v40, v172
	v_max3_f32 v128, v57, v41, v128
	v_max3_f32 v172, v58, v42, v172
	v_max3_f32 v128, v59, v43, v128
	v_mfma_f32_32x32x16_bf16 v[0:15], v[124:127], v[72:75], v[0:15]
	ds_read_b128 v[124:127], v155 offset:13312
	v_max3_f32 v172, v60, v44, v172
	v_max3_f32 v128, v61, v45, v128
	v_max3_f32 v172, v62, v46, v172
	v_max3_f32 v128, v63, v47, v128
	v_max_f32_e32 v128, v128, v172
	v_lshl_add_u64 v[130:131], v[130:131], 0, s[84:85]
	v_lshl_add_u64 v[180:181], v[180:181], 0, s[84:85]
	s_mov_b32 s0, s45
	s_add_i32 s45, s45, 2
	s_cmp_lt_u32 s0, s19
	s_cbranch_scc1 .Lgf_top
	s_branch .Lg_fold

;   DI void gload_k(int t) {
;     const int row0 = rowk0 + t * 64;
;     const u16* kt = Kb + (size_t)row0 * kpitch;
;     const u16* pt = KPEb + (size_t)row0 * 32;
; #pragma unroll
;     for (int q = 0; q < NKL; ++q) {
;       const int c = tid + 256 * q, cc = c % KCH;
;       rk[q] = ldg16(((DQK == 96 && cc >= 8) ? pt : kt) + koff[q]);
;     }
;   template <int PAR>
;   DI void step(int t, f32x16 (&cur)[2], f32x16 (&nxt)[2]) {
;     if (t + 1 < nt) sstore_k(PAR ^ 1);
;     if (t > 0) sstore_v(PAR);
;     __syncthreads();
;     if (t + 1 < nt) qk(PAR ^ 1, nxt);
;     float mx = fmaxf(cur[0][0], cur[1][0]);
; #pragma unroll
;     for (int i = 1; i < 16; ++i) mx = fmaxf(fmaxf(cur[0][i], cur[1][i]), mx);
;     if (__builtin_amdgcn_ballot_w64(mx > ATT_THR) != 0ull) {
;       asm volatile("" ::: "memory");
;       mx = fmaxf(mx, xhalf(mx));
;       const float want = mref + fmaxf(mx, 0.f);
;       const float mn = __uint_as_float(pack2(want, 0.f) << 16);
;       const float d = mn - mref;
;       const float alpha = __builtin_amdgcn_exp2f(-d);
;       mref = mn;
;       l *= alpha;
; #pragma unroll
;       for (int a = 0; a < 2; ++a)
; #pragma unroll
;         for (int i = 0; i < 16; ++i) { o[a][i] *= alpha; cur[a][i] -= d; nxt[a][i] -= d; }
;       u32x4 q4 = {h == 0 ? (pack2(-mn, 0.f) & 0xffffu) : 0u, 0u, 0u, 0u};
;       qm = __builtin_bit_cast(bf16x8, q4);
;     }
;     float psum = 0.f;
; #pragma unroll
;     for (int kb2 = 0; kb2 < 2; ++kb2)
; #pragma unroll
;       for (int i = 0; i < 16; ++i) { const float pv = __builtin_amdgcn_exp2f(cur[kb2][i]); cur[kb2][i] = pv; psum += pv; }
;     l += psum;
;     if (t + 2 < nt) gload_k(t + 2);
;     if (t + 1 < nt) gload_v(t + 1);
;     const u16* vb = sV + PAR * VBUF + r * GP + h * 8;
; #pragma unroll
;     for (int kb2 = 0; kb2 < 2; ++kb2)
; #pragma unroll
;       for (int s2 = 0; s2 < 2; ++s2) {
;         u32x4 pk = {pack2(cur[kb2][8 * s2], cur[kb2][8 * s2 + 1]), pack2(cur[kb2][8 * s2 + 2], cur[kb2][8 * s2 + 3]),
;                     pack2(cur[kb2][8 * s2 + 4], cur[kb2][8 * s2 + 5]), pack2(cur[kb2][8 * s2 + 6], cur[kb2][8 * s2 + 7])};
;         const bf16x8 pf = __builtin_bit_cast(bf16x8, pk);
; #pragma unroll
;         for (int db = 0; db < 2; ++db) {
;           const bf16x8 a = *(const bf16x8*)(vb + db * 32 * GP + kb2 * 32 + s2 * 16);
;           o[db] = MFMA(a, pf, o[db]);
;         }
;       }
;   }
.Lg_skipKA:
	ds_read_b128 v[96:99], v156 offset:18432
	ds_read_b128 v[100:103], v156 offset:22528
	ds_read_b128 v[104:107], v157 offset:18432
	ds_read_b128 v[108:111], v157 offset:22528
	v_mfma_f32_32x32x16_bf16 v[80:95], v[112:115], v[144:147], v[80:95]
	ds_read_b128 v[112:115], v158 offset:18432
	v_exp_f32_e32 v61, v61
	v_add_f32_e32 v183, v59, v183
	v_exp_f32_e32 v62, v62
	v_add_f32_e32 v182, v60, v182
	v_exp_f32_e32 v63, v63
	v_mfma_f32_32x32x16_bf16 v[64:79], v[116:119], v[144:147], v[64:79]
	ds_read_b128 v[116:119], v158 offset:22528
	v_add_f32_e32 v183, v61, v183
	v_cvt_pk_bf16_f32 v56, v56, v57
	v_add_f32_e32 v182, v62, v182
	v_cvt_pk_bf16_f32 v57, v58, v59
	v_add_f32_e32 v183, v63, v183
	v_mfma_f32_32x32x16_bf16 v[80:95], v[120:123], v[148:151], v[80:95]
	ds_read_b128 v[120:123], v159 offset:18432
	v_cvt_pk_bf16_f32 v58, v60, v61
	v_cvt_pk_bf16_f32 v59, v62, v63
	v_exp_f32_e32 v32, v32
	v_exp_f32_e32 v33, v33
	v_exp_f32_e32 v34, v34
	v_mfma_f32_32x32x16_bf16 v[64:79], v[124:127], v[148:151], v[64:79]
	ds_read_b128 v[124:127], v159 offset:22528
	v_add_f32_e32 v182, v32, v182
	v_exp_f32_e32 v35, v35
	v_add_f32_e32 v183, v33, v183
	v_exp_f32_e32 v36, v36
	v_add_f32_e32 v182, v34, v182
	s_add_i32 m0, s46, 27648
	s_nop 0
	global_load_lds_dwordx4 v[160:161], off
	global_load_lds_dwordx4 v[162:163], off offset:1024
	v_lshl_add_u64 v[160:161], v[160:161], 0, s[84:85]
	v_lshl_add_u64 v[162:163], v[162:163], 0, s[84:85]
	v_mfma_f32_32x32x16_bf16 v[80:95], v[132:135], v[168:171], v[80:95]
	v_exp_f32_e32 v37, v37
	v_add_f32_e32 v183, v35, v183
	v_exp_f32_e32 v38, v38
	v_add_f32_e32 v182, v36, v182
	v_exp_f32_e32 v39, v39
	v_mfma_f32_32x32x16_bf16 v[64:79], v[132:135], v[168:171], v[64:79]
	v_add_f32_e32 v183, v37, v183
	v_cvt_pk_bf16_f32 v32, v32, v33
	v_add_f32_e32 v182, v38, v182
	v_cvt_pk_bf16_f32 v33, v34, v35
	v_add_f32_e32 v183, v39, v183
	s_waitcnt lgkmcnt(4)
	v_mfma_f32_32x32x16_bf16 v[16:31], v[96:99], v[48:51], v[16:31]
	ds_read_b128 v[96:99], v152
	v_cvt_pk_bf16_f32 v34, v36, v37
	v_cvt_pk_bf16_f32 v35, v38, v39
	v_exp_f32_e32 v40, v40
	v_exp_f32_e32 v41, v41
	v_exp_f32_e32 v42, v42
	v_mfma_f32_32x32x16_bf16 v[0:15], v[100:103], v[48:51], v[0:15]
	ds_read_b128 v[100:103], v152 offset:4096
	v_add_f32_e32 v182, v40, v182
	v_exp_f32_e32 v43, v43
	v_add_f32_e32 v183, v41, v183
	v_exp_f32_e32 v44, v44
	v_add_f32_e32 v182, v42, v182
	v_mfma_f32_32x32x16_bf16 v[16:31], v[104:107], v[56:59], v[16:31]
	ds_read_b128 v[104:107], v153
	v_exp_f32_e32 v45, v45
	v_add_f32_e32 v183, v43, v183
	v_exp_f32_e32 v46, v46
	v_add_f32_e32 v182, v44, v182
	v_exp_f32_e32 v47, v47
	v_mfma_f32_32x32x16_bf16 v[0:15], v[108:111], v[56:59], v[0:15]
	ds_read_b128 v[108:111], v153 offset:4096
	v_add_f32_e32 v183, v45, v183
	v_cvt_pk_bf16_f32 v40, v40, v41
	v_add_f32_e32 v182, v46, v182
	v_cvt_pk_bf16_f32 v41, v42, v43
	v_add_f32_e32 v183, v47, v183
	s_waitcnt lgkmcnt(4)
	v_mfma_f32_32x32x16_bf16 v[16:31], v[112:115], v[32:35], v[16:31]
	ds_read_b128 v[112:115], v154
	v_cvt_pk_bf16_f32 v42, v44, v45
	v_cvt_pk_bf16_f32 v43, v46, v47
	v_max3_f32 v128, v80, v64, v81
	v_max3_f32 v172, v65, v82, v66
	v_max3_f32 v128, v83, v67, v128
	v_mfma_f32_32x32x16_bf16 v[0:15], v[116:119], v[32:35], v[0:15]
	ds_read_b128 v[116:119], v154 offset:4096
	v_max3_f32 v172, v84, v68, v172
	v_max3_f32 v128, v85, v69, v128
	v_max3_f32 v172, v86, v70, v172
	v_max3_f32 v128, v87, v71, v128
	v_max3_f32 v172, v88, v72, v172
	v_mfma_f32_32x32x16_bf16 v[16:31], v[120:123], v[40:43], v[16:31]
	ds_read_b128 v[120:123], v155
	v_max3_f32 v128, v89, v73, v128
	v_max3_f32 v172, v90, v74, v172
	v_max3_f32 v128, v91, v75, v128
	v_max3_f32 v172, v92, v76, v172
	v_mfma_f32_32x32x16_bf16 v[0:15], v[124:127], v[40:43], v[0:15]
	ds_read_b128 v[124:127], v155 offset:4096
	v_max3_f32 v128, v93, v77, v128
	v_max3_f32 v172, v94, v78, v172
	v_max3_f32 v128, v95, v79, v128
	v_max_f32_e32 v128, v128, v172
	v_cmp_lt_f32_e32 vcc, s65, v128
	s_cbranch_vccnz .Lg_rareB

; #define MFMA(a, b, c) __builtin_amdgcn_mfma_f32_32x32x16_bf16((a), (b), (c), 0, 0, 0)
; DI float xhalf(float v) { return __shfl_xor(v, 32); }
;   DI void gload_v(int t) {
;     const u16* vt = Vt + (rowk0 + t * 64);
; #pragma unroll
;     for (int q = 0; q < 2; ++q) rv[q] = ldg16(vt + voff[q]);
;   }
;   template <int PAR>
;   DI void step(int t, f32x16 (&cur)[2], f32x16 (&nxt)[2]) {
;     if (t + 1 < nt) sstore_k(PAR ^ 1);
;     if (t > 0) sstore_v(PAR);
;     __syncthreads();
;     if (t + 1 < nt) qk(PAR ^ 1, nxt);
;     float mx = fmaxf(cur[0][0], cur[1][0]);
; #pragma unroll
;     for (int i = 1; i < 16; ++i) mx = fmaxf(fmaxf(cur[0][i], cur[1][i]), mx);
;     if (__builtin_amdgcn_ballot_w64(mx > ATT_THR) != 0ull) {
;       asm volatile("" ::: "memory");
;       mx = fmaxf(mx, xhalf(mx));
;       const float want = mref + fmaxf(mx, 0.f);
;       const float mn = __uint_as_float(pack2(want, 0.f) << 16);
;       const float d = mn - mref;
;       const float alpha = __builtin_amdgcn_exp2f(-d);
;       mref = mn;
;       l *= alpha;
; #pragma unroll
;       for (int a = 0; a < 2; ++a)
; #pragma unroll
;         for (int i = 0; i < 16; ++i) { o[a][i] *= alpha; cur[a][i] -= d; nxt[a][i] -= d; }
;       u32x4 q4 = {h == 0 ? (pack2(-mn, 0.f) & 0xffffu) : 0u, 0u, 0u, 0u};
;       qm = __builtin_bit_cast(bf16x8, q4);
;     }
;     float psum = 0.f;
; #pragma unroll
;     for (int kb2 = 0; kb2 < 2; ++kb2)
; #pragma unroll
;       for (int i = 0; i < 16; ++i) { const float pv = __builtin_amdgcn_exp2f(cur[kb2][i]); cur[kb2][i] = pv; psum += pv; }
;     l += psum;
;     if (t + 2 < nt) gload_k(t + 2);
;     if (t + 1 < nt) gload_v(t + 1);
;     const u16* vb = sV + PAR * VBUF + r * GP + h * 8;
; #pragma unroll
;     for (int kb2 = 0; kb2 < 2; ++kb2)
; #pragma unroll
;       for (int s2 = 0; s2 < 2; ++s2) {
;         u32x4 pk = {pack2(cur[kb2][8 * s2], cur[kb2][8 * s2 + 1]), pack2(cur[kb2][8 * s2 + 2], cur[kb2][8 * s2 + 3]),
;                     pack2(cur[kb2][8 * s2 + 4], cur[kb2][8 * s2 + 5]), pack2(cur[kb2][8 * s2 + 6], cur[kb2][8 * s2 + 7])};
;         const bf16x8 pf = __builtin_bit_cast(bf16x8, pk);
; #pragma unroll
;         for (int db = 0; db < 2; ++db) {
;           const bf16x8 a = *(const bf16x8*)(vb + db * 32 * GP + kb2 * 32 + s2 * 16);
;           o[db] = MFMA(a, pf, o[db]);
;         }
;       }
;   }
.Lg_skipKB:
	ds_read_b128 v[96:99], v156 offset:27648
	ds_read_b128 v[100:103], v156 offset:31744
	ds_read_b128 v[104:107], v157 offset:27648
	ds_read_b128 v[108:111], v157 offset:31744
	v_mfma_f32_32x32x16_bf16 v[48:63], v[112:115], v[144:147], v[48:63]
	ds_read_b128 v[112:115], v158 offset:27648
	v_exp_f32_e32 v93, v93
	v_add_f32_e32 v183, v91, v183
	v_exp_f32_e32 v94, v94
	v_add_f32_e32 v182, v92, v182
	v_exp_f32_e32 v95, v95
	v_mfma_f32_32x32x16_bf16 v[32:47], v[116:119], v[144:147], v[32:47]
	ds_read_b128 v[116:119], v158 offset:31744
	v_add_f32_e32 v183, v93, v183
	v_cvt_pk_bf16_f32 v88, v88, v89
	v_add_f32_e32 v182, v94, v182
	v_cvt_pk_bf16_f32 v89, v90, v91
	v_add_f32_e32 v183, v95, v183
	v_mfma_f32_32x32x16_bf16 v[48:63], v[120:123], v[148:151], v[48:63]
	ds_read_b128 v[120:123], v159 offset:27648
	v_cvt_pk_bf16_f32 v90, v92, v93
	v_cvt_pk_bf16_f32 v91, v94, v95
	v_exp_f32_e32 v64, v64
	v_exp_f32_e32 v65, v65
	v_exp_f32_e32 v66, v66
	v_mfma_f32_32x32x16_bf16 v[32:47], v[124:127], v[148:151], v[32:47]
	ds_read_b128 v[124:127], v159 offset:31744
	v_add_f32_e32 v182, v64, v182
	v_exp_f32_e32 v67, v67
	v_add_f32_e32 v183, v65, v183
	v_exp_f32_e32 v68, v68
	v_add_f32_e32 v182, v66, v182
	s_cmp_ge_u32 s45, s19
	s_cbranch_scc1 .Lg_lastVB
	s_add_i32 m0, s46, 18432
	s_nop 0
	global_load_lds_dwordx4 v[164:165], off
	global_load_lds_dwordx4 v[166:167], off offset:1024
	v_lshl_add_u64 v[164:165], v[164:165], 0, s[84:85]
	v_lshl_add_u64 v[166:167], v[166:167], 0, s[84:85]
	s_branch .Lg_skipVB

; #define MFMA(a, b, c) __builtin_amdgcn_mfma_f32_32x32x16_bf16((a), (b), (c), 0, 0, 0)
; DI unsigned pack2(float a, float b) { f32x2v f = {a, b}; bf16x2v v = __builtin_convertvector(f, bf16x2v); return __builtin_bit_cast(unsigned, v); }
;   DI void qk(int buf, f32x16 (&s)[2]) {
;     ...
;     s[0] = MFMA(kone, qm, s[0]);
;     s[1] = MFMA(kone, qm, s[1]);
;   }
;   template <int PAR>
;   DI void step(int t, f32x16 (&cur)[2], f32x16 (&nxt)[2]) {
;     if (t + 1 < nt) sstore_k(PAR ^ 1);
;     if (t > 0) sstore_v(PAR);
;     __syncthreads();
;     if (t + 1 < nt) qk(PAR ^ 1, nxt);
;     float mx = fmaxf(cur[0][0], cur[1][0]);
; #pragma unroll
;     for (int i = 1; i < 16; ++i) mx = fmaxf(fmaxf(cur[0][i], cur[1][i]), mx);
;     if (__builtin_amdgcn_ballot_w64(mx > ATT_THR) != 0ull) {
;       asm volatile("" ::: "memory");
;       mx = fmaxf(mx, xhalf(mx));
;       const float want = mref + fmaxf(mx, 0.f);
;       const float mn = __uint_as_float(pack2(want, 0.f) << 16);
;       const float d = mn - mref;
;       const float alpha = __builtin_amdgcn_exp2f(-d);
;       mref = mn;
;       l *= alpha;
; #pragma unroll
;       for (int a = 0; a < 2; ++a)
; #pragma unroll
;         for (int i = 0; i < 16; ++i) { o[a][i] *= alpha; cur[a][i] -= d; nxt[a][i] -= d; }
;       u32x4 q4 = {h == 0 ? (pack2(-mn, 0.f) & 0xffffu) : 0u, 0u, 0u, 0u};
;       qm = __builtin_bit_cast(bf16x8, q4);
;     }
;     float psum = 0.f;
; #pragma unroll
;     for (int kb2 = 0; kb2 < 2; ++kb2)
; #pragma unroll
;       for (int i = 0; i < 16; ++i) { const float pv = __builtin_amdgcn_exp2f(cur[kb2][i]); cur[kb2][i] = pv; psum += pv; }
;     l += psum;
;     if (t + 2 < nt) gload_k(t + 2);
;     if (t + 1 < nt) gload_v(t + 1);
;     const u16* vb = sV + PAR * VBUF + r * GP + h * 8;
; #pragma unroll
;     for (int kb2 = 0; kb2 < 2; ++kb2)
; #pragma unroll
;       for (int s2 = 0; s2 < 2; ++s2) {
;         u32x4 pk = {pack2(cur[kb2][8 * s2], cur[kb2][8 * s2 + 1]), pack2(cur[kb2][8 * s2 + 2], cur[kb2][8 * s2 + 3]),
;                     pack2(cur[kb2][8 * s2 + 4], cur[kb2][8 * s2 + 5]), pack2(cur[kb2][8 * s2 + 6], cur[kb2][8 * s2 + 7])};
;         const bf16x8 pf = __builtin_bit_cast(bf16x8, pk);
; #pragma unroll
;         for (int db = 0; db < 2; ++db) {
;           const bf16x8 a = *(const bf16x8*)(vb + db * 32 * GP + kb2 * 32 + s2 * 16);
;           o[db] = MFMA(a, pf, o[db]);
;         }
;       }
.Lg_skipVB:
	v_mfma_f32_32x32x16_bf16 v[48:63], v[132:135], v[168:171], v[48:63]
	v_exp_f32_e32 v69, v69
	v_add_f32_e32 v183, v67, v183
	v_exp_f32_e32 v70, v70
	v_add_f32_e32 v182, v68, v182
	v_exp_f32_e32 v71, v71
	v_mfma_f32_32x32x16_bf16 v[32:47], v[132:135], v[168:171], v[32:47]
	v_add_f32_e32 v183, v69, v183
	v_cvt_pk_bf16_f32 v64, v64, v65
	v_add_f32_e32 v182, v70, v182
	v_cvt_pk_bf16_f32 v65, v66, v67
	v_add_f32_e32 v183, v71, v183
	s_waitcnt lgkmcnt(4)
	v_mfma_f32_32x32x16_bf16 v[16:31], v[96:99], v[80:83], v[16:31]
	ds_read_b128 v[96:99], v152 offset:9216
	v_cvt_pk_bf16_f32 v66, v68, v69
	v_cvt_pk_bf16_f32 v67, v70, v71
	v_exp_f32_e32 v72, v72
	v_exp_f32_e32 v73, v73
	v_exp_f32_e32 v74, v74
	v_mfma_f32_32x32x16_bf16 v[0:15], v[100:103], v[80:83], v[0:15]
	ds_read_b128 v[100:103], v152 offset:13312
	v_add_f32_e32 v182, v72, v182
	v_exp_f32_e32 v75, v75
	v_add_f32_e32 v183, v73, v183
	v_exp_f32_e32 v76, v76
	v_add_f32_e32 v182, v74, v182
	v_mfma_f32_32x32x16_bf16 v[16:31], v[104:107], v[88:91], v[16:31]
	ds_read_b128 v[104:107], v153 offset:9216
	v_exp_f32_e32 v77, v77
	v_add_f32_e32 v183, v75, v183
	v_exp_f32_e32 v78, v78
	v_add_f32_e32 v182, v76, v182
	v_exp_f32_e32 v79, v79
	v_mfma_f32_32x32x16_bf16 v[0:15], v[108:111], v[88:91], v[0:15]
	ds_read_b128 v[108:111], v153 offset:13312
	v_add_f32_e32 v183, v77, v183
	v_cvt_pk_bf16_f32 v72, v72, v73
	v_add_f32_e32 v182, v78, v182
	v_cvt_pk_bf16_f32 v73, v74, v75
	v_add_f32_e32 v183, v79, v183
	s_waitcnt lgkmcnt(4)
	v_mfma_f32_32x32x16_bf16 v[16:31], v[112:115], v[64:67], v[16:31]
	ds_read_b128 v[112:115], v154 offset:9216
	v_cvt_pk_bf16_f32 v74, v76, v77
	v_cvt_pk_bf16_f32 v75, v78, v79
	v_max3_f32 v128, v48, v32, v49
	v_max3_f32 v172, v33, v50, v34
	v_max3_f32 v128, v51, v35, v128
	v_mfma_f32_32x32x16_bf16 v[0:15], v[116:119], v[64:67], v[0:15]
	ds_read_b128 v[116:119], v154 offset:13312
	v_max3_f32 v172, v52, v36, v172
	v_max3_f32 v128, v53, v37, v128
	v_max3_f32 v172, v54, v38, v172
	v_max3_f32 v128, v55, v39, v128
	v_max3_f32 v172, v56, v40, v172
	v_mfma_f32_32x32x16_bf16 v[16:31], v[120:123], v[72:75], v[16:31]
	ds_read_b128 v[120:123], v155 offset:9216
	v_max3_f32 v128, v57, v41, v128
	v_max3_f32 v172, v58, v42, v172
	v_max3_f32 v128, v59, v43, v128
	v_max3_f32 v172, v60, v44, v172
	v_mfma_f32_32x32x16_bf16 v[0:15], v[124:127], v[72:75], v[0:15]
	ds_read_b128 v[124:127], v155 offset:13312
	v_max3_f32 v128, v61, v45, v128
	v_max3_f32 v172, v62, v46, v172
	v_max3_f32 v128, v63, v47, v128
	v_max_f32_e32 v128, v128, v172
	v_lshl_add_u64 v[130:131], v[130:131], 0, s[84:85]
	v_lshl_add_u64 v[180:181], v[180:181], 0, s[84:85]
	s_mov_b32 s0, s45
	s_add_i32 s45, s45, 2
	s_cmp_lt_u32 s0, s19
	s_cbranch_scc1 .LBB0_238
	s_branch .Lg_fold

; #define MFMA(a, b, c) __builtin_amdgcn_mfma_f32_32x32x16_bf16((a), (b), (c), 0, 0, 0)
; DI unsigned pack2(float a, float b) { f32x2v f = {a, b}; bf16x2v v = __builtin_convertvector(f, bf16x2v); return __builtin_bit_cast(unsigned, v); }
; DI float xhalf(float v) { return __shfl_xor(v, 32); }
;   template <int PAR>
;   DI void step(int t, f32x16 (&cur)[2], f32x16 (&nxt)[2]) {
;     if (t + 1 < nt) sstore_k(PAR ^ 1);
;     if (t > 0) sstore_v(PAR);
;     __syncthreads();
;     if (t + 1 < nt) qk(PAR ^ 1, nxt);
;     float mx = fmaxf(cur[0][0], cur[1][0]);
; #pragma unroll
;     for (int i = 1; i < 16; ++i) mx = fmaxf(fmaxf(cur[0][i], cur[1][i]), mx);
;     if (__builtin_amdgcn_ballot_w64(mx > ATT_THR) != 0ull) {
;       asm volatile("" ::: "memory");
;       mx = fmaxf(mx, xhalf(mx));
;       const float want = mref + fmaxf(mx, 0.f);
;       const float mn = __uint_as_float(pack2(want, 0.f) << 16);
;       const float d = mn - mref;
;       const float alpha = __builtin_amdgcn_exp2f(-d);
;       mref = mn;
;       l *= alpha;
; #pragma unroll
;       for (int a = 0; a < 2; ++a)
; #pragma unroll
;         for (int i = 0; i < 16; ++i) { o[a][i] *= alpha; cur[a][i] -= d; nxt[a][i] -= d; }
;       u32x4 q4 = {h == 0 ? (pack2(-mn, 0.f) & 0xffffu) : 0u, 0u, 0u, 0u};
;       qm = __builtin_bit_cast(bf16x8, q4);
;     }
;     float psum = 0.f;
; #pragma unroll
;     for (int kb2 = 0; kb2 < 2; ++kb2)
; #pragma unroll
;       for (int i = 0; i < 16; ++i) { const float pv = __builtin_amdgcn_exp2f(cur[kb2][i]); cur[kb2][i] = pv; psum += pv; }
;     l += psum;
;     if (t + 2 < nt) gload_k(t + 2);
;     if (t + 1 < nt) gload_v(t + 1);
;     const u16* vb = sV + PAR * VBUF + r * GP + h * 8;
; #pragma unroll
;     for (int kb2 = 0; kb2 < 2; ++kb2)
; #pragma unroll
;       for (int s2 = 0; s2 < 2; ++s2) {
;         u32x4 pk = {pack2(cur[kb2][8 * s2], cur[kb2][8 * s2 + 1]), pack2(cur[kb2][8 * s2 + 2], cur[kb2][8 * s2 + 3]),
;                     pack2(cur[kb2][8 * s2 + 4], cur[kb2][8 * s2 + 5]), pack2(cur[kb2][8 * s2 + 6], cur[kb2][8 * s2 + 7])};
;         const bf16x8 pf = __builtin_bit_cast(bf16x8, pk);
; #pragma unroll
;         for (int db = 0; db < 2; ++db) {
;           const bf16x8 a = *(const bf16x8*)(vb + db * 32 * GP + kb2 * 32 + s2 * 16);
;           o[db] = MFMA(a, pf, o[db]);
;         }
;       }
.Lmf_skipKA:
	v_mfma_f32_32x32x16_bf16 v[80:95], v[112:115], v[144:147], v[80:95]
	ds_read_b128 v[112:115], v166 offset:25600
	v_exp_f32_e32 v61, v61
	v_add_f32_e32 v239, v59, v239
	v_exp_f32_e32 v62, v62
	v_add_f32_e32 v238, v60, v238
	v_exp_f32_e32 v63, v63
	v_mfma_f32_32x32x16_bf16 v[64:79], v[116:119], v[144:147], v[64:79]
	ds_read_b128 v[116:119], v166 offset:29696
	v_add_f32_e32 v239, v61, v239
	v_cvt_pk_bf16_f32 v56, v56, v57
	v_add_f32_e32 v238, v62, v238
	v_cvt_pk_bf16_f32 v57, v58, v59
	v_add_f32_e32 v239, v63, v239
	v_mfma_f32_32x32x16_bf16 v[80:95], v[120:123], v[148:151], v[80:95]
	ds_read_b128 v[120:123], v167 offset:25600
	v_cvt_pk_bf16_f32 v58, v60, v61
	v_cvt_pk_bf16_f32 v59, v62, v63
	v_exp_f32_e32 v32, v32
	v_exp_f32_e32 v33, v33
	v_exp_f32_e32 v34, v34
	v_mfma_f32_32x32x16_bf16 v[64:79], v[124:127], v[148:151], v[64:79]
	ds_read_b128 v[124:127], v167 offset:29696
	v_add_f32_e32 v238, v32, v238
	v_exp_f32_e32 v35, v35
	v_add_f32_e32 v239, v33, v239
	v_exp_f32_e32 v36, v36
	v_add_f32_e32 v238, v34, v238
	v_mfma_f32_32x32x16_bf16 v[80:95], v[96:99], v[152:155], v[80:95]
	ds_read_b128 v[96:99], v168 offset:25600
	v_exp_f32_e32 v37, v37
	v_add_f32_e32 v239, v35, v239
	v_exp_f32_e32 v38, v38
	v_add_f32_e32 v238, v36, v238
	v_mfma_f32_32x32x16_bf16 v[64:79], v[100:103], v[152:155], v[64:79]
	ds_read_b128 v[100:103], v168 offset:29696
	v_exp_f32_e32 v39, v39
	v_add_f32_e32 v239, v37, v239
	v_cvt_pk_bf16_f32 v32, v32, v33
	v_add_f32_e32 v238, v38, v238
	s_add_i32 m0, s44, 36864
	s_nop 0
	global_load_lds_dwordx4 v[176:177], off
	global_load_lds_dwordx4 v[178:179], off offset:1024
	v_mfma_f32_32x32x16_bf16 v[80:95], v[104:107], v[156:159], v[80:95]
	ds_read_b128 v[104:107], v169 offset:25600
	v_cvt_pk_bf16_f32 v33, v34, v35
	v_add_f32_e32 v239, v39, v239
	v_cvt_pk_bf16_f32 v34, v36, v37
	v_cvt_pk_bf16_f32 v35, v38, v39
	v_mfma_f32_32x32x16_bf16 v[64:79], v[108:111], v[156:159], v[64:79]
	ds_read_b128 v[108:111], v169 offset:29696
	v_exp_f32_e32 v40, v40
	v_exp_f32_e32 v41, v41
	v_exp_f32_e32 v42, v42
	v_add_f32_e32 v238, v40, v238
	s_waitcnt lgkmcnt(4)
	v_mfma_f32_32x32x16_bf16 v[16:31], v[112:115], v[48:51], v[16:31]
	ds_read_b128 v[112:115], v162
	v_exp_f32_e32 v43, v43
	v_add_f32_e32 v239, v41, v239
	v_exp_f32_e32 v44, v44
	v_add_f32_e32 v238, v42, v238
	v_mfma_f32_32x32x16_bf16 v[0:15], v[116:119], v[48:51], v[0:15]
	ds_read_b128 v[116:119], v162 offset:4096
	v_exp_f32_e32 v45, v45
	v_add_f32_e32 v239, v43, v239
	v_exp_f32_e32 v46, v46
	v_add_f32_e32 v238, v44, v238
	v_mfma_f32_32x32x16_bf16 v[16:31], v[120:123], v[56:59], v[16:31]
	ds_read_b128 v[120:123], v163
	v_exp_f32_e32 v47, v47
	v_add_f32_e32 v239, v45, v239
	v_cvt_pk_bf16_f32 v40, v40, v41
	v_add_f32_e32 v238, v46, v238
	v_mfma_f32_32x32x16_bf16 v[0:15], v[124:127], v[56:59], v[0:15]
	ds_read_b128 v[124:127], v163 offset:4096
	v_cvt_pk_bf16_f32 v41, v42, v43
	v_add_f32_e32 v239, v47, v239
	v_cvt_pk_bf16_f32 v42, v44, v45
	v_cvt_pk_bf16_f32 v43, v46, v47
	s_waitcnt lgkmcnt(4)
	v_mfma_f32_32x32x16_bf16 v[16:31], v[96:99], v[32:35], v[16:31]
	ds_read_b128 v[96:99], v160
	v_max3_f32 v240, v80, v64, v81
	v_max3_f32 v241, v65, v82, v66
	v_max3_f32 v240, v83, v67, v240
	v_max3_f32 v241, v84, v68, v241
	v_mfma_f32_32x32x16_bf16 v[0:15], v[100:103], v[32:35], v[0:15]
	ds_read_b128 v[100:103], v160 offset:4096
	v_max3_f32 v240, v85, v69, v240
	v_max3_f32 v241, v86, v70, v241
	v_max3_f32 v240, v87, v71, v240
	v_max3_f32 v241, v88, v72, v241
	v_mfma_f32_32x32x16_bf16 v[16:31], v[104:107], v[40:43], v[16:31]
	ds_read_b128 v[104:107], v161
	v_max3_f32 v240, v89, v73, v240
	v_max3_f32 v241, v90, v74, v241
	v_max3_f32 v240, v91, v75, v240
	v_max3_f32 v241, v92, v76, v241
	v_mfma_f32_32x32x16_bf16 v[0:15], v[108:111], v[40:43], v[0:15]
	ds_read_b128 v[108:111], v161 offset:4096
	v_max3_f32 v240, v93, v77, v240
	v_max3_f32 v241, v94, v78, v241
	v_max3_f32 v240, v95, v79, v240
	v_max_f32_e32 v240, v240, v241
	v_cmp_lt_f32_e32 vcc, s65, v240
	s_cbranch_vccnz .Lmf_rareB

; #define MFMA(a, b, c) __builtin_amdgcn_mfma_f32_32x32x16_bf16((a), (b), (c), 0, 0, 0)
; DI unsigned pack2(float a, float b) { f32x2v f = {a, b}; bf16x2v v = __builtin_convertvector(f, bf16x2v); return __builtin_bit_cast(unsigned, v); }
;   template <int PAR>
;   DI void step(int t, f32x16 (&cur)[2], f32x16 (&nxt)[2]) {
;     ...
;     float psum = 0.f;
; #pragma unroll
;     for (int kb2 = 0; kb2 < 2; ++kb2)
; #pragma unroll
;       for (int i = 0; i < 16; ++i) { const float pv = __builtin_amdgcn_exp2f(cur[kb2][i]); cur[kb2][i] = pv; psum += pv; }
;     l += psum;
;     if (t + 2 < nt) gload_k(t + 2);
;     if (t + 1 < nt) gload_v(t + 1);
;     const u16* vb = sV + PAR * VBUF + r * GP + h * 8;
; #pragma unroll
;     for (int kb2 = 0; kb2 < 2; ++kb2)
; #pragma unroll
;       for (int s2 = 0; s2 < 2; ++s2) {
;         u32x4 pk = {pack2(cur[kb2][8 * s2], cur[kb2][8 * s2 + 1]), pack2(cur[kb2][8 * s2 + 2], cur[kb2][8 * s2 + 3]),
;                     pack2(cur[kb2][8 * s2 + 4], cur[kb2][8 * s2 + 5]), pack2(cur[kb2][8 * s2 + 6], cur[kb2][8 * s2 + 7])};
;         const bf16x8 pf = __builtin_bit_cast(bf16x8, pk);
; #pragma unroll
;         for (int db = 0; db < 2; ++db) {
;           const bf16x8 a = *(const bf16x8*)(vb + db * 32 * GP + kb2 * 32 + s2 * 16);
;           o[db] = MFMA(a, pf, o[db]);
;         }
;       }
.Lmf_skipKB:
	v_mfma_f32_32x32x16_bf16 v[48:63], v[112:115], v[144:147], v[48:63]
	ds_read_b128 v[112:115], v166 offset:36864
	v_exp_f32_e32 v93, v93
	v_add_f32_e32 v239, v91, v239
	v_exp_f32_e32 v94, v94
	v_add_f32_e32 v238, v92, v238
	v_exp_f32_e32 v95, v95
	v_mfma_f32_32x32x16_bf16 v[32:47], v[116:119], v[144:147], v[32:47]
	ds_read_b128 v[116:119], v166 offset:40960
	v_add_f32_e32 v239, v93, v239
	v_cvt_pk_bf16_f32 v88, v88, v89
	v_add_f32_e32 v238, v94, v238
	v_cvt_pk_bf16_f32 v89, v90, v91
	v_add_f32_e32 v239, v95, v239
	v_mfma_f32_32x32x16_bf16 v[48:63], v[120:123], v[148:151], v[48:63]
	ds_read_b128 v[120:123], v167 offset:36864
	v_cvt_pk_bf16_f32 v90, v92, v93
	v_cvt_pk_bf16_f32 v91, v94, v95
	v_exp_f32_e32 v64, v64
	v_exp_f32_e32 v65, v65
	v_exp_f32_e32 v66, v66
	v_mfma_f32_32x32x16_bf16 v[32:47], v[124:127], v[148:151], v[32:47]
	ds_read_b128 v[124:127], v167 offset:40960
	v_add_f32_e32 v238, v64, v238
	v_exp_f32_e32 v67, v67
	v_add_f32_e32 v239, v65, v239
	v_exp_f32_e32 v68, v68
	v_add_f32_e32 v238, v66, v238
	v_mfma_f32_32x32x16_bf16 v[48:63], v[96:99], v[152:155], v[48:63]
	ds_read_b128 v[96:99], v168 offset:36864
	v_exp_f32_e32 v69, v69
	v_add_f32_e32 v239, v67, v239
	v_exp_f32_e32 v70, v70
	v_add_f32_e32 v238, v68, v238
	v_mfma_f32_32x32x16_bf16 v[32:47], v[100:103], v[152:155], v[32:47]
	ds_read_b128 v[100:103], v168 offset:40960
	v_exp_f32_e32 v71, v71
	v_add_f32_e32 v239, v69, v239
	v_cvt_pk_bf16_f32 v64, v64, v65
	v_add_f32_e32 v238, v70, v238
	s_cmp_ge_u32 s31, s19
	s_cbranch_scc1 .Lmf_lastVB
	s_add_i32 m0, s44, 25472
	s_nop 0
	global_load_lds_dwordx4 v[176:177], off offset:128
	global_load_lds_dwordx4 v[178:179], off offset:1152
	v_lshl_add_u64 v[176:177], v[176:177], 0, s[84:85]
	v_lshl_add_u64 v[178:179], v[178:179], 0, s[84:85]
	s_branch .Lmf_skipVB

; #define MFMA(a, b, c) __builtin_amdgcn_mfma_f32_32x32x16_bf16((a), (b), (c), 0, 0, 0)
; DI unsigned pack2(float a, float b) { f32x2v f = {a, b}; bf16x2v v = __builtin_convertvector(f, bf16x2v); return __builtin_bit_cast(unsigned, v); }
; DI float xhalf(float v) { return __shfl_xor(v, 32); }
;   template <int PAR>
;   DI void step(int t, f32x16 (&cur)[2], f32x16 (&nxt)[2]) {
;     if (t + 1 < nt) sstore_k(PAR ^ 1);
;     if (t > 0) sstore_v(PAR);
;     __syncthreads();
;     if (t + 1 < nt) qk(PAR ^ 1, nxt);
;     float mx = fmaxf(cur[0][0], cur[1][0]);
; #pragma unroll
;     for (int i = 1; i < 16; ++i) mx = fmaxf(fmaxf(cur[0][i], cur[1][i]), mx);
;     if (__builtin_amdgcn_ballot_w64(mx > ATT_THR) != 0ull) {
;       asm volatile("" ::: "memory");
;       mx = fmaxf(mx, xhalf(mx));
;       const float want = mref + fmaxf(mx, 0.f);
;       const float mn = __uint_as_float(pack2(want, 0.f) << 16);
;       const float d = mn - mref;
;       const float alpha = __builtin_amdgcn_exp2f(-d);
;       mref = mn;
;       l *= alpha;
; #pragma unroll
;       for (int a = 0; a < 2; ++a)
; #pragma unroll
;         for (int i = 0; i < 16; ++i) { o[a][i] *= alpha; cur[a][i] -= d; nxt[a][i] -= d; }
;       u32x4 q4 = {h == 0 ? (pack2(-mn, 0.f) & 0xffffu) : 0u, 0u, 0u, 0u};
;       qm = __builtin_bit_cast(bf16x8, q4);
;     }
;     float psum = 0.f;
; #pragma unroll
;     for (int kb2 = 0; kb2 < 2; ++kb2)
; #pragma unroll
;       for (int i = 0; i < 16; ++i) { const float pv = __builtin_amdgcn_exp2f(cur[kb2][i]); cur[kb2][i] = pv; psum += pv; }
;     l += psum;
;     if (t + 2 < nt) gload_k(t + 2);
;     if (t + 1 < nt) gload_v(t + 1);
;     const u16* vb = sV + PAR * VBUF + r * GP + h * 8;
; #pragma unroll
;     for (int kb2 = 0; kb2 < 2; ++kb2)
; #pragma unroll
;       for (int s2 = 0; s2 < 2; ++s2) {
;         u32x4 pk = {pack2(cur[kb2][8 * s2], cur[kb2][8 * s2 + 1]), pack2(cur[kb2][8 * s2 + 2], cur[kb2][8 * s2 + 3]),
;                     pack2(cur[kb2][8 * s2 + 4], cur[kb2][8 * s2 + 5]), pack2(cur[kb2][8 * s2 + 6], cur[kb2][8 * s2 + 7])};
;         const bf16x8 pf = __builtin_bit_cast(bf16x8, pk);
; #pragma unroll
;         for (int db = 0; db < 2; ++db) {
;           const bf16x8 a = *(const bf16x8*)(vb + db * 32 * GP + kb2 * 32 + s2 * 16);
;           o[db] = MFMA(a, pf, o[db]);
;         }
;       }
.Lmf_skipVB:
	v_mfma_f32_32x32x16_bf16 v[48:63], v[104:107], v[156:159], v[48:63]
	ds_read_b128 v[104:107], v169 offset:36864
	v_cvt_pk_bf16_f32 v65, v66, v67
	v_add_f32_e32 v239, v71, v239
	v_cvt_pk_bf16_f32 v66, v68, v69
	v_cvt_pk_bf16_f32 v67, v70, v71
	v_mfma_f32_32x32x16_bf16 v[32:47], v[108:111], v[156:159], v[32:47]
	ds_read_b128 v[108:111], v169 offset:40960
	v_exp_f32_e32 v72, v72
	v_exp_f32_e32 v73, v73
	v_exp_f32_e32 v74, v74
	v_add_f32_e32 v238, v72, v238
	s_waitcnt lgkmcnt(4)
	v_mfma_f32_32x32x16_bf16 v[16:31], v[112:115], v[80:83], v[16:31]
	ds_read_b128 v[112:115], v162 offset:13312
	v_exp_f32_e32 v75, v75
	v_add_f32_e32 v239, v73, v239
	v_exp_f32_e32 v76, v76
	v_add_f32_e32 v238, v74, v238
	v_mfma_f32_32x32x16_bf16 v[0:15], v[116:119], v[80:83], v[0:15]
	ds_read_b128 v[116:119], v162 offset:17408
	v_exp_f32_e32 v77, v77
	v_add_f32_e32 v239, v75, v239
	v_exp_f32_e32 v78, v78
	v_add_f32_e32 v238, v76, v238
	v_mfma_f32_32x32x16_bf16 v[16:31], v[120:123], v[88:91], v[16:31]
	ds_read_b128 v[120:123], v163 offset:13312
	v_exp_f32_e32 v79, v79
	v_add_f32_e32 v239, v77, v239
	v_cvt_pk_bf16_f32 v72, v72, v73
	v_add_f32_e32 v238, v78, v238
	v_mfma_f32_32x32x16_bf16 v[0:15], v[124:127], v[88:91], v[0:15]
	ds_read_b128 v[124:127], v163 offset:17408
	v_cvt_pk_bf16_f32 v73, v74, v75
	v_add_f32_e32 v239, v79, v239
	v_cvt_pk_bf16_f32 v74, v76, v77
	v_cvt_pk_bf16_f32 v75, v78, v79
	s_waitcnt lgkmcnt(4)
	v_mfma_f32_32x32x16_bf16 v[16:31], v[96:99], v[64:67], v[16:31]
	ds_read_b128 v[96:99], v160 offset:13312
	v_max3_f32 v240, v48, v32, v49
	v_max3_f32 v241, v33, v50, v34
	v_max3_f32 v240, v51, v35, v240
	v_max3_f32 v241, v52, v36, v241
	v_mfma_f32_32x32x16_bf16 v[0:15], v[100:103], v[64:67], v[0:15]
	ds_read_b128 v[100:103], v160 offset:17408
	v_max3_f32 v240, v53, v37, v240
	v_max3_f32 v241, v54, v38, v241
	v_max3_f32 v240, v55, v39, v240
	v_max3_f32 v241, v56, v40, v241
	v_mfma_f32_32x32x16_bf16 v[16:31], v[104:107], v[72:75], v[16:31]
	ds_read_b128 v[104:107], v161 offset:13312
	v_max3_f32 v240, v57, v41, v240
	v_max3_f32 v241, v58, v42, v241
	v_max3_f32 v240, v59, v43, v240
	v_max3_f32 v241, v60, v44, v241
	v_mfma_f32_32x32x16_bf16 v[0:15], v[108:111], v[72:75], v[0:15]
	ds_read_b128 v[108:111], v161 offset:17408
	v_max3_f32 v240, v61, v45, v240
	v_max3_f32 v241, v62, v46, v241
	v_max3_f32 v240, v63, v47, v240
	v_max_f32_e32 v240, v240, v241
	v_lshl_add_u64 v[130:131], v[130:131], 0, s[84:85]
	v_lshl_add_u64 v[220:221], v[220:221], 0, s[84:85]
	s_mov_b32 s0, s31
	s_add_i32 s31, s31, 2
	s_cmp_lt_u32 s0, s19
	s_cbranch_scc1 .Lmf_top
	s_branch .Lm_fold

; #define MFMA(a, b, c) __builtin_amdgcn_mfma_f32_32x32x16_bf16((a), (b), (c), 0, 0, 0)
; DI unsigned pack2(float a, float b) { f32x2v f = {a, b}; bf16x2v v = __builtin_convertvector(f, bf16x2v); return __builtin_bit_cast(unsigned, v); }
; DI float xhalf(float v) { return __shfl_xor(v, 32); }
;   template <int PAR>
;   DI void step(int t, f32x16 (&cur)[2], f32x16 (&nxt)[2]) {
;     if (t + 1 < nt) sstore_k(PAR ^ 1);
;     if (t > 0) sstore_v(PAR);
;     __syncthreads();
;     if (t + 1 < nt) qk(PAR ^ 1, nxt);
;     float mx = fmaxf(cur[0][0], cur[1][0]);
; #pragma unroll
;     for (int i = 1; i < 16; ++i) mx = fmaxf(fmaxf(cur[0][i], cur[1][i]), mx);
;     if (__builtin_amdgcn_ballot_w64(mx > ATT_THR) != 0ull) {
;       asm volatile("" ::: "memory");
;       mx = fmaxf(mx, xhalf(mx));
;       const float want = mref + fmaxf(mx, 0.f);
;       const float mn = __uint_as_float(pack2(want, 0.f) << 16);
;       const float d = mn - mref;
;       const float alpha = __builtin_amdgcn_exp2f(-d);
;       mref = mn;
;       l *= alpha;
; #pragma unroll
;       for (int a = 0; a < 2; ++a)
; #pragma unroll
;         for (int i = 0; i < 16; ++i) { o[a][i] *= alpha; cur[a][i] -= d; nxt[a][i] -= d; }
;       u32x4 q4 = {h == 0 ? (pack2(-mn, 0.f) & 0xffffu) : 0u, 0u, 0u, 0u};
;       qm = __builtin_bit_cast(bf16x8, q4);
;     }
;     float psum = 0.f;
; #pragma unroll
;     for (int kb2 = 0; kb2 < 2; ++kb2)
; #pragma unroll
;       for (int i = 0; i < 16; ++i) { const float pv = __builtin_amdgcn_exp2f(cur[kb2][i]); cur[kb2][i] = pv; psum += pv; }
;     l += psum;
;     if (t + 2 < nt) gload_k(t + 2);
;     if (t + 1 < nt) gload_v(t + 1);
;     const u16* vb = sV + PAR * VBUF + r * GP + h * 8;
; #pragma unroll
;     for (int kb2 = 0; kb2 < 2; ++kb2)
; #pragma unroll
;       for (int s2 = 0; s2 < 2; ++s2) {
;         u32x4 pk = {pack2(cur[kb2][8 * s2], cur[kb2][8 * s2 + 1]), pack2(cur[kb2][8 * s2 + 2], cur[kb2][8 * s2 + 3]),
;                     pack2(cur[kb2][8 * s2 + 4], cur[kb2][8 * s2 + 5]), pack2(cur[kb2][8 * s2 + 6], cur[kb2][8 * s2 + 7])};
;         const bf16x8 pf = __builtin_bit_cast(bf16x8, pk);
; #pragma unroll
;         for (int db = 0; db < 2; ++db) {
;           const bf16x8 a = *(const bf16x8*)(vb + db * 32 * GP + kb2 * 32 + s2 * 16);
;           o[db] = MFMA(a, pf, o[db]);
;         }
;       }
.Lm_skipKA:
	v_mfma_f32_32x32x16_bf16 v[80:95], v[112:115], v[144:147], v[80:95]
	ds_read_b128 v[112:115], v166 offset:25600
	v_exp_f32_e32 v59, v59
	v_add_f32_e32 v239, v57, v239
	v_exp_f32_e32 v60, v60
	v_add_f32_e32 v238, v58, v238
	v_mfma_f32_32x32x16_bf16 v[64:79], v[116:119], v[144:147], v[64:79]
	ds_read_b128 v[116:119], v166 offset:29696
	v_exp_f32_e32 v61, v61
	v_add_f32_e32 v239, v59, v239
	v_exp_f32_e32 v62, v62
	v_add_f32_e32 v238, v60, v238
	v_mfma_f32_32x32x16_bf16 v[80:95], v[120:123], v[148:151], v[80:95]
	ds_read_b128 v[120:123], v167 offset:25600
	v_exp_f32_e32 v63, v63
	v_add_f32_e32 v239, v61, v239
	v_cvt_pk_bf16_f32 v56, v56, v57
	v_add_f32_e32 v238, v62, v238
	v_mfma_f32_32x32x16_bf16 v[64:79], v[124:127], v[148:151], v[64:79]
	ds_read_b128 v[124:127], v167 offset:29696
	v_cvt_pk_bf16_f32 v57, v58, v59
	v_add_f32_e32 v239, v63, v239
	v_cvt_pk_bf16_f32 v58, v60, v61
	v_cvt_pk_bf16_f32 v59, v62, v63
	v_mfma_f32_32x32x16_bf16 v[80:95], v[96:99], v[152:155], v[80:95]
	ds_read_b128 v[96:99], v168 offset:25600
	v_exp_f32_e32 v32, v32
	v_exp_f32_e32 v33, v33
	v_exp_f32_e32 v34, v34
	v_add_f32_e32 v238, v32, v238
	v_mfma_f32_32x32x16_bf16 v[64:79], v[100:103], v[152:155], v[64:79]
	ds_read_b128 v[100:103], v168 offset:29696
	v_exp_f32_e32 v35, v35
	v_add_f32_e32 v239, v33, v239
	v_exp_f32_e32 v36, v36
	v_add_f32_e32 v238, v34, v238
	s_add_i32 m0, s44, 36864
	s_nop 0
	global_load_lds_dwordx4 v[176:177], off
	global_load_lds_dwordx4 v[178:179], off offset:1024
	v_mfma_f32_32x32x16_bf16 v[80:95], v[104:107], v[156:159], v[80:95]
	ds_read_b128 v[104:107], v169 offset:25600
	v_exp_f32_e32 v37, v37
	v_add_f32_e32 v239, v35, v239
	v_exp_f32_e32 v38, v38
	v_add_f32_e32 v238, v36, v238
	v_mfma_f32_32x32x16_bf16 v[64:79], v[108:111], v[156:159], v[64:79]
	ds_read_b128 v[108:111], v169 offset:29696
	v_exp_f32_e32 v39, v39
	v_add_f32_e32 v239, v37, v239
	v_cvt_pk_bf16_f32 v32, v32, v33
	v_add_f32_e32 v238, v38, v238
	v_mfma_f32_32x32x16_bf16 v[80:95], v[132:135], v[180:183], v[80:95]
	v_cvt_pk_bf16_f32 v33, v34, v35
	v_add_f32_e32 v239, v39, v239
	v_cvt_pk_bf16_f32 v34, v36, v37
	v_cvt_pk_bf16_f32 v35, v38, v39
	v_mfma_f32_32x32x16_bf16 v[64:79], v[132:135], v[180:183], v[64:79]
	v_exp_f32_e32 v40, v40
	v_exp_f32_e32 v41, v41
	v_exp_f32_e32 v42, v42
	v_add_f32_e32 v238, v40, v238
	s_waitcnt lgkmcnt(4)
	v_mfma_f32_32x32x16_bf16 v[16:31], v[112:115], v[48:51], v[16:31]
	ds_read_b128 v[112:115], v162
	v_exp_f32_e32 v43, v43
	v_add_f32_e32 v239, v41, v239
	v_exp_f32_e32 v44, v44
	v_add_f32_e32 v238, v42, v238
	v_mfma_f32_32x32x16_bf16 v[0:15], v[116:119], v[48:51], v[0:15]
	ds_read_b128 v[116:119], v162 offset:4096
	v_exp_f32_e32 v45, v45
	v_add_f32_e32 v239, v43, v239
	v_exp_f32_e32 v46, v46
	v_add_f32_e32 v238, v44, v238
	v_mfma_f32_32x32x16_bf16 v[16:31], v[120:123], v[56:59], v[16:31]
	ds_read_b128 v[120:123], v163
	v_exp_f32_e32 v47, v47
	v_add_f32_e32 v239, v45, v239
	v_cvt_pk_bf16_f32 v40, v40, v41
	v_add_f32_e32 v238, v46, v238
	v_mfma_f32_32x32x16_bf16 v[0:15], v[124:127], v[56:59], v[0:15]
	ds_read_b128 v[124:127], v163 offset:4096
	v_cvt_pk_bf16_f32 v41, v42, v43
	v_add_f32_e32 v239, v47, v239
	v_cvt_pk_bf16_f32 v42, v44, v45
	v_cvt_pk_bf16_f32 v43, v46, v47
	s_waitcnt lgkmcnt(4)
	v_mfma_f32_32x32x16_bf16 v[16:31], v[96:99], v[32:35], v[16:31]
	ds_read_b128 v[96:99], v160
	v_max3_f32 v240, v80, v64, v81
	v_max3_f32 v241, v65, v82, v66
	v_max3_f32 v240, v83, v67, v240
	v_max3_f32 v241, v84, v68, v241
	v_mfma_f32_32x32x16_bf16 v[0:15], v[100:103], v[32:35], v[0:15]
	ds_read_b128 v[100:103], v160 offset:4096
	v_max3_f32 v240, v85, v69, v240
	v_max3_f32 v241, v86, v70, v241
	v_max3_f32 v240, v87, v71, v240
	v_max3_f32 v241, v88, v72, v241
	v_mfma_f32_32x32x16_bf16 v[16:31], v[104:107], v[40:43], v[16:31]
	ds_read_b128 v[104:107], v161
	v_max3_f32 v240, v89, v73, v240
	v_max3_f32 v241, v90, v74, v241
	v_max3_f32 v240, v91, v75, v240
	v_max3_f32 v241, v92, v76, v241
	v_mfma_f32_32x32x16_bf16 v[0:15], v[108:111], v[40:43], v[0:15]
	ds_read_b128 v[108:111], v161 offset:4096
	v_max3_f32 v240, v93, v77, v240
	v_max3_f32 v241, v94, v78, v241
	v_max3_f32 v240, v95, v79, v240
	v_max_f32_e32 v240, v240, v241
	v_cmp_lt_f32_e32 vcc, s65, v240
	s_cbranch_vccnz .Lm_rareB

; #define MFMA(a, b, c) __builtin_amdgcn_mfma_f32_32x32x16_bf16((a), (b), (c), 0, 0, 0)
; DI unsigned pack2(float a, float b) { f32x2v f = {a, b}; bf16x2v v = __builtin_convertvector(f, bf16x2v); return __builtin_bit_cast(unsigned, v); }
;   template <int PAR>
;   DI void step(int t, f32x16 (&cur)[2], f32x16 (&nxt)[2]) {
;     ...
;     float psum = 0.f;
; #pragma unroll
;     for (int kb2 = 0; kb2 < 2; ++kb2)
; #pragma unroll
;       for (int i = 0; i < 16; ++i) { const float pv = __builtin_amdgcn_exp2f(cur[kb2][i]); cur[kb2][i] = pv; psum += pv; }
;     l += psum;
;     if (t + 2 < nt) gload_k(t + 2);
;     if (t + 1 < nt) gload_v(t + 1);
;     const u16* vb = sV + PAR * VBUF + r * GP + h * 8;
; #pragma unroll
;     for (int kb2 = 0; kb2 < 2; ++kb2)
; #pragma unroll
;       for (int s2 = 0; s2 < 2; ++s2) {
;         u32x4 pk = {pack2(cur[kb2][8 * s2], cur[kb2][8 * s2 + 1]), pack2(cur[kb2][8 * s2 + 2], cur[kb2][8 * s2 + 3]),
;                     pack2(cur[kb2][8 * s2 + 4], cur[kb2][8 * s2 + 5]), pack2(cur[kb2][8 * s2 + 6], cur[kb2][8 * s2 + 7])};
;         const bf16x8 pf = __builtin_bit_cast(bf16x8, pk);
; #pragma unroll
;         for (int db = 0; db < 2; ++db) {
;           const bf16x8 a = *(const bf16x8*)(vb + db * 32 * GP + kb2 * 32 + s2 * 16);
;           o[db] = MFMA(a, pf, o[db]);
;         }
;       }
.Lm_skipKB:
	v_mfma_f32_32x32x16_bf16 v[48:63], v[112:115], v[144:147], v[48:63]
	ds_read_b128 v[112:115], v166 offset:36864
	v_exp_f32_e32 v91, v91
	v_add_f32_e32 v239, v89, v239
	v_exp_f32_e32 v92, v92
	v_add_f32_e32 v238, v90, v238
	v_mfma_f32_32x32x16_bf16 v[32:47], v[116:119], v[144:147], v[32:47]
	ds_read_b128 v[116:119], v166 offset:40960
	v_exp_f32_e32 v93, v93
	v_add_f32_e32 v239, v91, v239
	v_exp_f32_e32 v94, v94
	v_add_f32_e32 v238, v92, v238
	v_mfma_f32_32x32x16_bf16 v[48:63], v[120:123], v[148:151], v[48:63]
	ds_read_b128 v[120:123], v167 offset:36864
	v_exp_f32_e32 v95, v95
	v_add_f32_e32 v239, v93, v239
	v_cvt_pk_bf16_f32 v88, v88, v89
	v_add_f32_e32 v238, v94, v238
	v_mfma_f32_32x32x16_bf16 v[32:47], v[124:127], v[148:151], v[32:47]
	ds_read_b128 v[124:127], v167 offset:40960
	v_cvt_pk_bf16_f32 v89, v90, v91
	v_add_f32_e32 v239, v95, v239
	v_cvt_pk_bf16_f32 v90, v92, v93
	v_cvt_pk_bf16_f32 v91, v94, v95
	v_mfma_f32_32x32x16_bf16 v[48:63], v[96:99], v[152:155], v[48:63]
	ds_read_b128 v[96:99], v168 offset:36864
	v_exp_f32_e32 v64, v64
	v_exp_f32_e32 v65, v65
	v_exp_f32_e32 v66, v66
	v_add_f32_e32 v238, v64, v238
	v_mfma_f32_32x32x16_bf16 v[32:47], v[100:103], v[152:155], v[32:47]
	ds_read_b128 v[100:103], v168 offset:40960
	v_exp_f32_e32 v67, v67
	v_add_f32_e32 v239, v65, v239
	v_exp_f32_e32 v68, v68
	v_add_f32_e32 v238, v66, v238
	s_cmp_ge_u32 s31, s19
	s_cbranch_scc1 .Lm_lastVB
	s_add_i32 m0, s44, 25472
	s_nop 0
	global_load_lds_dwordx4 v[176:177], off offset:128
	global_load_lds_dwordx4 v[178:179], off offset:1152
	v_lshl_add_u64 v[176:177], v[176:177], 0, s[84:85]
	v_lshl_add_u64 v[178:179], v[178:179], 0, s[84:85]
	s_branch .Lm_skipVB

; #define MFMA(a, b, c) __builtin_amdgcn_mfma_f32_32x32x16_bf16((a), (b), (c), 0, 0, 0)
; DI unsigned pack2(float a, float b) { f32x2v f = {a, b}; bf16x2v v = __builtin_convertvector(f, bf16x2v); return __builtin_bit_cast(unsigned, v); }
; DI float xhalf(float v) { return __shfl_xor(v, 32); }
;   template <int PAR>
;   DI void step(int t, f32x16 (&cur)[2], f32x16 (&nxt)[2]) {
;     if (t + 1 < nt) sstore_k(PAR ^ 1);
;     if (t > 0) sstore_v(PAR);
;     __syncthreads();
;     if (t + 1 < nt) qk(PAR ^ 1, nxt);
;     float mx = fmaxf(cur[0][0], cur[1][0]);
; #pragma unroll
;     for (int i = 1; i < 16; ++i) mx = fmaxf(fmaxf(cur[0][i], cur[1][i]), mx);
;     if (__builtin_amdgcn_ballot_w64(mx > ATT_THR) != 0ull) {
;       asm volatile("" ::: "memory");
;       mx = fmaxf(mx, xhalf(mx));
;       const float want = mref + fmaxf(mx, 0.f);
;       const float mn = __uint_as_float(pack2(want, 0.f) << 16);
;       const float d = mn - mref;
;       const float alpha = __builtin_amdgcn_exp2f(-d);
;       mref = mn;
;       l *= alpha;
; #pragma unroll
;       for (int a = 0; a < 2; ++a)
; #pragma unroll
;         for (int i = 0; i < 16; ++i) { o[a][i] *= alpha; cur[a][i] -= d; nxt[a][i] -= d; }
;       u32x4 q4 = {h == 0 ? (pack2(-mn, 0.f) & 0xffffu) : 0u, 0u, 0u, 0u};
;       qm = __builtin_bit_cast(bf16x8, q4);
;     }
;     float psum = 0.f;
; #pragma unroll
;     for (int kb2 = 0; kb2 < 2; ++kb2)
; #pragma unroll
;       for (int i = 0; i < 16; ++i) { const float pv = __builtin_amdgcn_exp2f(cur[kb2][i]); cur[kb2][i] = pv; psum += pv; }
;     l += psum;
;     if (t + 2 < nt) gload_k(t + 2);
;     if (t + 1 < nt) gload_v(t + 1);
;     const u16* vb = sV + PAR * VBUF + r * GP + h * 8;
; #pragma unroll
;     for (int kb2 = 0; kb2 < 2; ++kb2)
; #pragma unroll
;       for (int s2 = 0; s2 < 2; ++s2) {
;         u32x4 pk = {pack2(cur[kb2][8 * s2], cur[kb2][8 * s2 + 1]), pack2(cur[kb2][8 * s2 + 2], cur[kb2][8 * s2 + 3]),
;                     pack2(cur[kb2][8 * s2 + 4], cur[kb2][8 * s2 + 5]), pack2(cur[kb2][8 * s2 + 6], cur[kb2][8 * s2 + 7])};
;         const bf16x8 pf = __builtin_bit_cast(bf16x8, pk);
; #pragma unroll
;         for (int db = 0; db < 2; ++db) {
;           const bf16x8 a = *(const bf16x8*)(vb + db * 32 * GP + kb2 * 32 + s2 * 16);
;           o[db] = MFMA(a, pf, o[db]);
;         }
;       }
.Lm_skipVB:
	v_mfma_f32_32x32x16_bf16 v[48:63], v[104:107], v[156:159], v[48:63]
	ds_read_b128 v[104:107], v169 offset:36864
	v_exp_f32_e32 v69, v69
	v_add_f32_e32 v239, v67, v239
	v_exp_f32_e32 v70, v70
	v_add_f32_e32 v238, v68, v238
	v_mfma_f32_32x32x16_bf16 v[32:47], v[108:111], v[156:159], v[32:47]
	ds_read_b128 v[108:111], v169 offset:40960
	v_exp_f32_e32 v71, v71
	v_add_f32_e32 v239, v69, v239
	v_cvt_pk_bf16_f32 v64, v64, v65
	v_add_f32_e32 v238, v70, v238
	v_mfma_f32_32x32x16_bf16 v[48:63], v[132:135], v[180:183], v[48:63]
	v_cvt_pk_bf16_f32 v65, v66, v67
	v_add_f32_e32 v239, v71, v239
	v_cvt_pk_bf16_f32 v66, v68, v69
	v_cvt_pk_bf16_f32 v67, v70, v71
	v_mfma_f32_32x32x16_bf16 v[32:47], v[132:135], v[180:183], v[32:47]
	v_exp_f32_e32 v72, v72
	v_exp_f32_e32 v73, v73
	v_exp_f32_e32 v74, v74
	v_add_f32_e32 v238, v72, v238
	s_waitcnt lgkmcnt(4)
	v_mfma_f32_32x32x16_bf16 v[16:31], v[112:115], v[80:83], v[16:31]
	ds_read_b128 v[112:115], v162 offset:13312
	v_exp_f32_e32 v75, v75
	v_add_f32_e32 v239, v73, v239
	v_exp_f32_e32 v76, v76
	v_add_f32_e32 v238, v74, v238
	v_mfma_f32_32x32x16_bf16 v[0:15], v[116:119], v[80:83], v[0:15]
	ds_read_b128 v[116:119], v162 offset:17408
	v_exp_f32_e32 v77, v77
	v_add_f32_e32 v239, v75, v239
	v_exp_f32_e32 v78, v78
	v_add_f32_e32 v238, v76, v238
	v_mfma_f32_32x32x16_bf16 v[16:31], v[120:123], v[88:91], v[16:31]
	ds_read_b128 v[120:123], v163 offset:13312
	v_exp_f32_e32 v79, v79
	v_add_f32_e32 v239, v77, v239
	v_cvt_pk_bf16_f32 v72, v72, v73
	v_add_f32_e32 v238, v78, v238
	v_mfma_f32_32x32x16_bf16 v[0:15], v[124:127], v[88:91], v[0:15]
	ds_read_b128 v[124:127], v163 offset:17408
	v_cvt_pk_bf16_f32 v73, v74, v75
	v_add_f32_e32 v239, v79, v239
	v_cvt_pk_bf16_f32 v74, v76, v77
	v_cvt_pk_bf16_f32 v75, v78, v79
	s_waitcnt lgkmcnt(4)
	v_mfma_f32_32x32x16_bf16 v[16:31], v[96:99], v[64:67], v[16:31]
	ds_read_b128 v[96:99], v160 offset:13312
	v_max3_f32 v240, v48, v32, v49
	v_max3_f32 v241, v33, v50, v34
	v_max3_f32 v240, v51, v35, v240
	v_max3_f32 v241, v52, v36, v241
	v_mfma_f32_32x32x16_bf16 v[0:15], v[100:103], v[64:67], v[0:15]
	ds_read_b128 v[100:103], v160 offset:17408
	v_max3_f32 v240, v53, v37, v240
	v_max3_f32 v241, v54, v38, v241
	v_max3_f32 v240, v55, v39, v240
	v_max3_f32 v241, v56, v40, v241
	v_mfma_f32_32x32x16_bf16 v[16:31], v[104:107], v[72:75], v[16:31]
	ds_read_b128 v[104:107], v161 offset:13312
	v_max3_f32 v240, v57, v41, v240
	v_max3_f32 v241, v58, v42, v241
	v_max3_f32 v240, v59, v43, v240
	v_max3_f32 v241, v60, v44, v241
	v_mfma_f32_32x32x16_bf16 v[0:15], v[108:111], v[72:75], v[0:15]
	ds_read_b128 v[108:111], v161 offset:17408
	v_max3_f32 v240, v61, v45, v240
	v_max3_f32 v241, v62, v46, v241
	v_max3_f32 v240, v63, v47, v240
	v_max_f32_e32 v240, v240, v241
	v_lshl_add_u64 v[130:131], v[130:131], 0, s[84:85]
	v_lshl_add_u64 v[220:221], v[220:221], 0, s[84:85]
	s_mov_b32 s0, s31
	s_add_i32 s31, s31, 2
	s_cmp_lt_u32 s0, s19
	s_cbranch_scc1 .LBB0_268
	s_branch .Lm_fold
